# NSA: selected-block unions via DPP row reductions instead of 44 serial ds_bpermute; first selected tile prefetched before top-k
# speedup vs baseline: 1.0064x; 1.0036x over previous
; #define GAS __attribute__((address_space(1)))
; DI float xhalf_sum(float v) { const auto rr = __builtin_amdgcn_permlane32_swap(__float_as_uint(v), __float_as_uint(v), false, false); return __uint_as_float(rr[0]) + __uint_as_float(rr[1]); }
; DI void stage_load(StageRegs& R, const bf16* Kb, int kstride, const bf16* Vt, int vstride, int tid, bool withV) {
;     const int rw = tid >> 3, ch = tid & 7;
;     R.k = *(const GAS u32x4*)((const GAS bf16*)Kb + (size_t)rw * kstride + ch * 8);
;     if (withV) R.v = *(const GAS u32x4*)((const GAS bf16*)Vt + (size_t)rw * vstride + ch * 8);
; }
; DI void nsa_unit(const bf16* PR, const bf16* VT, const bf16* kcb, const bf16* vctb, bf16* Y, LAS unsigned char* lds, int b, int g, int jt) {
;     ...
;         const float l = xhalf_sum(f.l);
;         const float inv_l = l > 0.f ? 1.f / l : 0.f;
;         if (hi == 0) invl[hq * 64 + tl] = inv_l;
;         const float gs = g0 * inv_l;
; #pragma unroll
;         for (int i = 0; i < 16; ++i) { acc0[i] = gs * f.o0[i]; acc1[i] = gs * f.o1[i]; }
;     }
;     __syncthreads();
;     {
;         const int tok = 8 * wid + (lane >> 3), sub = lane & 7;
;         float v[16]; unsigned selbits = 0u;
; #pragma unroll
;         for (int k = 0; k < 16; ++k) { const int j = 16 * sub + k;
;             const bool valid = j <= jt, forced = (j == 0) || (j == jt) || (j == jt - 1);
;             float s = -1.f;
;             if (valid && !forced) s = (imp[((size_t)0 * 64 + tok) * IMP_PITCH + j] * invl[0 * 64 + tok] + imp[((size_t)1 * 64 + tok) * IMP_PITCH + j] * invl[1 * 64 + tok])
;                                     + (imp[((size_t)2 * 64 + tok) * IMP_PITCH + j] * invl[2 * 64 + tok] + imp[((size_t)3 * 64 + tok) * IMP_PITCH + j] * invl[3 * 64 + tok]);
;             if (valid && (forced || jt < 16)) selbits |= 1u << k;
;             v[k] = s; }
.LBB0_931:
	v_mov_b32_e32 v1, v127
	s_nop 1
	v_permlane32_swap_b32_e32 v127, v1
	v_add_f32_e32 v1, v127, v1
	v_div_scale_f32 v2, s[0:1], v1, v1, 1.0
	v_rcp_f32_e32 v3, v2
	s_nop 0
	v_fma_f32 v4, -v2, v3, 1.0
	v_fmac_f32_e32 v3, v4, v3
	v_div_scale_f32 v4, vcc, 1.0, v1, 1.0
	v_mul_f32_e32 v5, v4, v3
	v_fma_f32 v6, -v2, v5, v4
	v_fmac_f32_e32 v5, v6, v3
	v_fma_f32 v2, -v2, v5, v4
	v_div_fmas_f32 v2, v2, v3, v5
	v_div_fixup_f32 v2, v2, v1, 1.0
	v_cmp_lt_f32_e32 vcc, 0, v1
	s_nop 1
	v_cndmask_b32_e32 v246, 0, v2, vcc
	v_cmp_gt_u32_e32 vcc, 32, v118
	s_and_saveexec_b64 s[4:5], vcc
	s_lshl_b32 s0, s47, 8
	s_add_i32 s0, s0, 0
	v_lshl_add_u32 v1, v111, 2, s0
	v_add_u32_e32 v1, 0x20800, v1
	ds_write_b32 v1, v246
	s_or_b64 exec, exec, s[4:5]
	s_mov_b32 s4, s72
	s_mov_b32 s5, 0
	s_lshl_b64 s[6:7], s[4:5], 13
	v_readlane_b32 s8, v254, 41
	v_readlane_b32 s9, v254, 42
	s_add_u32 s6, s8, s6
	s_addc_u32 s7, s9, s7
	s_lshl_b32 s8, s72, 6
	s_mov_b32 s9, 0
	s_lshl_b64 s[8:9], s[8:9], 1
	v_readlane_b32 s12, v254, 43
	v_readlane_b32 s13, v254, 44
	s_add_u32 s8, s12, s8
	s_addc_u32 s9, s13, s9
	v_lshl_add_u64 v[136:137], s[6:7], 0, v[168:169]
	v_lshlrev_b32_e32 v138, 1, v110
	v_mov_b32_e32 v139, v0
	v_lshlrev_b64 v[140:141], 14, v[108:109]
	v_lshl_add_u64 v[136:137], v[136:137], 0, v[138:139]
	v_lshl_add_u64 v[140:141], s[8:9], 0, v[140:141]
	v_lshl_add_u64 v[140:141], v[140:141], 0, v[138:139]
	global_load_dwordx4 v[128:131], v[136:137], off
	global_load_dwordx4 v[132:135], v[140:141], off
	v_and_b32_e32 v2, 7, v119
	v_lshrrev_b32_e32 v1, 3, v118
	v_lshlrev_b32_e32 v3, 4, v2
	v_readlane_b32 s0, v255, 0
	v_lshl_or_b32 v1, s46, 3, v1
	s_sub_i32 s0, 0x9e, s0
	v_cmp_eq_u32_e64 s[6:7], 0, v2
	v_cmp_eq_u32_e64 s[8:9], s72, v3
	v_mul_lo_u32 v4, v1, s50
	s_or_b64 s[2:3], s[6:7], s[8:9]
	v_cmp_eq_u32_e64 s[6:7], s0, v3
	v_add_u32_e32 v7, 0, v4
	s_add_i32 s1, 0, 0x20800
	v_cmp_lt_u32_e32 vcc, s72, v3
	s_or_b64 s[4:5], s[2:3], s[6:7]
	v_lshl_add_u32 v57, v1, 2, s1
	v_add_u32_e32 v58, 0x10200, v7
	v_add_u32_e32 v56, 0x18300, v7
	s_nor_b64 s[2:3], vcc, s[4:5]
	v_mov_b32_e32 v4, -1.0
	v_mov_b32_e32 v5, -1.0
	s_waitcnt lgkmcnt(0)
	s_barrier
	s_and_saveexec_b64 s[6:7], s[2:3]
	s_cbranch_execz .LBB0_935
	v_lshlrev_b32_e32 v5, 2, v3
	v_add_u32_e32 v6, v7, v5
	ds_read2st64_b32 v[8:9], v6 offset1:129
	v_add_u32_e32 v6, v58, v5
	ds_read2st64_b32 v[10:11], v57 offset1:1
	ds_read2st64_b32 v[12:13], v57 offset0:2 offset1:3
	v_add_u32_e32 v5, v56, v5
	ds_read_b32 v15, v6
	ds_read_b32 v49, v5
	s_waitcnt lgkmcnt(4)
	v_mov_b32_e32 v48, v9
	v_mov_b32_e32 v14, v8
	s_waitcnt lgkmcnt(2)
	v_mov_b32_e32 v51, v12
	v_mov_b32_e32 v12, v11
	v_mov_b32_e32 v50, v10
	s_waitcnt lgkmcnt(0)
	v_pk_mul_f32 v[8:9], v[48:49], v[12:13]
	s_nop 0
	v_pk_fma_f32 v[8:9], v[14:15], v[50:51], v[8:9]
	s_nop 0
	v_add_f32_e32 v5, v8, v9

; #define LAS __attribute__((address_space(3)))
; DI void nsa_unit(const bf16* PR, const bf16* VT, const bf16* kcb, const bf16* vctb, bf16* Y, LAS unsigned char* lds, int b, int g, int jt) {
;     ...
;         ((LAS unsigned short*)selm)[tok * 8 + sub] = (unsigned short)selbits;
;     }
;     __syncthreads();
;     {
;         unsigned mk0, mk1, mk2, mk3, wu0, wu1, wu2, wu3, gu0, gu1, gu2, gu3;
;         { unsigned mk[4], wu[4], gu[4];
; #pragma unroll
;           for (int w = 0; w < 4; ++w) { mk[w] = selm[tl * 4 + w]; unsigned u = mk[w];
; #pragma unroll
;               for (int off = 1; off < 32; off <<= 1) u |= (unsigned)__shfl_xor((int)u, off);
;               wu[w] = __builtin_amdgcn_readfirstlane(u);
;               unsigned u2 = selm[lane * 4 + w];
; #pragma unroll
;               for (int off = 1; off < 64; off <<= 1) u2 |= (unsigned)__shfl_xor((int)u2, off);
;               gu[w] = __builtin_amdgcn_readfirstlane(u2); }
;           mk0 = mk[0]; mk1 = mk[1]; mk2 = mk[2]; mk3 = mk[3]; wu0 = wu[0]; wu1 = wu[1]; wu2 = wu[2]; wu3 = wu[3]; gu0 = gu[0]; gu1 = gu[1]; gu2 = gu[2]; gu3 = gu[3]; }
.LBB0_982:
	v_lshlrev_b32_e32 v1, 4, v1
	v_lshlrev_b32_e32 v2, 1, v2
	v_readlane_b32 s0, v254, 10
	v_xor_b32_e32 v3, 1, v219
	s_nop 0
	v_add3_u32 v1, s0, v1, v2
	ds_write_b16 v1, v56
	v_lshl_add_u32 v1, v111, 4, s0
	s_waitcnt lgkmcnt(0)
	s_barrier
	ds_read_b128 v[112:115], v1
	v_lshl_add_u32 v2, v118, 4, s0
	ds_read_b128 v[2:5], v2
	s_waitcnt lgkmcnt(0)
	v_mov_b32_e32 v6, v112
	v_mov_b32_e32 v7, v113
	v_mov_b32_e32 v8, v114
	v_mov_b32_e32 v9, v115
	v_or_b32_dpp v2, v2, v2 row_ror:1 row_mask:0xf bank_mask:0xf
	v_or_b32_dpp v3, v3, v3 row_ror:1 row_mask:0xf bank_mask:0xf
	v_or_b32_dpp v4, v4, v4 row_ror:1 row_mask:0xf bank_mask:0xf
	v_or_b32_dpp v5, v5, v5 row_ror:1 row_mask:0xf bank_mask:0xf
	v_or_b32_dpp v6, v6, v6 row_ror:1 row_mask:0xf bank_mask:0xf
	v_or_b32_dpp v7, v7, v7 row_ror:1 row_mask:0xf bank_mask:0xf
	v_or_b32_dpp v8, v8, v8 row_ror:1 row_mask:0xf bank_mask:0xf
	v_or_b32_dpp v9, v9, v9 row_ror:1 row_mask:0xf bank_mask:0xf
	v_or_b32_dpp v2, v2, v2 row_ror:2 row_mask:0xf bank_mask:0xf
	v_or_b32_dpp v3, v3, v3 row_ror:2 row_mask:0xf bank_mask:0xf
	v_or_b32_dpp v4, v4, v4 row_ror:2 row_mask:0xf bank_mask:0xf
	v_or_b32_dpp v5, v5, v5 row_ror:2 row_mask:0xf bank_mask:0xf
	v_or_b32_dpp v6, v6, v6 row_ror:2 row_mask:0xf bank_mask:0xf
	v_or_b32_dpp v7, v7, v7 row_ror:2 row_mask:0xf bank_mask:0xf
	v_or_b32_dpp v8, v8, v8 row_ror:2 row_mask:0xf bank_mask:0xf
	v_or_b32_dpp v9, v9, v9 row_ror:2 row_mask:0xf bank_mask:0xf
	v_or_b32_dpp v2, v2, v2 row_ror:4 row_mask:0xf bank_mask:0xf
	v_or_b32_dpp v3, v3, v3 row_ror:4 row_mask:0xf bank_mask:0xf
	v_or_b32_dpp v4, v4, v4 row_ror:4 row_mask:0xf bank_mask:0xf
	v_or_b32_dpp v5, v5, v5 row_ror:4 row_mask:0xf bank_mask:0xf
	v_or_b32_dpp v6, v6, v6 row_ror:4 row_mask:0xf bank_mask:0xf
	v_or_b32_dpp v7, v7, v7 row_ror:4 row_mask:0xf bank_mask:0xf
	v_or_b32_dpp v8, v8, v8 row_ror:4 row_mask:0xf bank_mask:0xf
	v_or_b32_dpp v9, v9, v9 row_ror:4 row_mask:0xf bank_mask:0xf
	v_or_b32_dpp v2, v2, v2 row_ror:8 row_mask:0xf bank_mask:0xf
	v_or_b32_dpp v3, v3, v3 row_ror:8 row_mask:0xf bank_mask:0xf
	v_or_b32_dpp v4, v4, v4 row_ror:8 row_mask:0xf bank_mask:0xf
	v_or_b32_dpp v5, v5, v5 row_ror:8 row_mask:0xf bank_mask:0xf
	v_or_b32_dpp v6, v6, v6 row_ror:8 row_mask:0xf bank_mask:0xf
	v_or_b32_dpp v7, v7, v7 row_ror:8 row_mask:0xf bank_mask:0xf
	v_or_b32_dpp v8, v8, v8 row_ror:8 row_mask:0xf bank_mask:0xf
	v_or_b32_dpp v9, v9, v9 row_ror:8 row_mask:0xf bank_mask:0xf
	v_readlane_b32 s54, v2, 0
	v_readlane_b32 s55, v2, 16
	v_readlane_b32 s56, v2, 32
	v_readlane_b32 s57, v2, 48
	v_readlane_b32 s58, v3, 0
	v_readlane_b32 s59, v3, 16
	v_readlane_b32 s60, v3, 32
	v_readlane_b32 s61, v3, 48
	v_readlane_b32 s62, v4, 0
	v_readlane_b32 s63, v4, 16
	v_readlane_b32 s64, v4, 32
	v_readlane_b32 s65, v4, 48
	v_readlane_b32 s66, v5, 0
	v_readlane_b32 s67, v5, 16
	v_readlane_b32 s68, v5, 32
	v_readlane_b32 s69, v5, 48
	s_or_b32 s54, s54, s55
	s_or_b32 s56, s56, s57
	s_or_b32 s58, s58, s59
	s_or_b32 s60, s60, s61
	s_or_b32 s62, s62, s63
	s_or_b32 s64, s64, s65
	s_or_b32 s66, s66, s67
	s_or_b32 s68, s68, s69
	s_or_b32 s47, s54, s56
	s_or_b32 s49, s58, s60
	s_or_b32 s51, s62, s64
	s_or_b32 s69, s66, s68
	v_readlane_b32 s54, v6, 0
	v_readlane_b32 s55, v6, 16
	v_readlane_b32 s56, v7, 0
	v_readlane_b32 s57, v7, 16
	v_readlane_b32 s58, v8, 0
	v_readlane_b32 s59, v8, 16
	v_readlane_b32 s60, v9, 0
	v_readlane_b32 s61, v9, 16
	s_or_b32 s46, s54, s55
	s_or_b32 s48, s56, s57
	s_or_b32 s50, s58, s59
	s_or_b32 s52, s60, s61
	s_mov_b32 s0, s69
	s_cmp_lg_u32 s0, 0
	s_cbranch_scc0 .LBB0_984
	s_mov_b64 s[4:5], 0
	s_mov_b32 s1, 3
	s_branch .LBB0_987

; #define GAS __attribute__((address_space(1)))
; #define LAS __attribute__((address_space(3)))
; DI void stage_load(StageRegs& R, const bf16* Kb, int kstride, const bf16* Vt, int vstride, int tid, bool withV) {
;     const int rw = tid >> 3, ch = tid & 7;
;     R.k = *(const GAS u32x4*)((const GAS bf16*)Kb + (size_t)rw * kstride + ch * 8);
;     if (withV) R.v = *(const GAS u32x4*)((const GAS bf16*)Vt + (size_t)rw * vstride + ch * 8);
; }
; DI void stage_store(LAS unsigned char* buf, const StageRegs& R, int tid, bool withV) {
;     const int rw = tid >> 3, ch = tid & 7;
;     *(LAS u32x4*)(buf + rw * 144 + ch * 16) = R.k;
;     if (withV) { LAS u32x2* p = (LAS u32x2*)(buf + KB_BYTES + rw * 136 + ch * 16); u32x2 a, b2; a.x = R.v.x; a.y = R.v.y; b2.x = R.v.z; b2.y = R.v.w; p[0] = a; p[1] = b2; }
; }
; DI void nsa_unit(const bf16* PR, const bf16* VT, const bf16* kcb, const bf16* vctb, bf16* Y, LAS unsigned char* lds, int b, int g, int jt) {
;     ...
;         int jcur; SEL_NEXT(jcur);
;         stage_load(R, ks + (size_t)jcur * 64 * 64, 64, vst + 64 * jcur, SEQ, tid, true); stage_store(tb, R, tid, true); __syncthreads();
;         int par = 0;
.LBB0_987:
	s_flbit_i32_b32 s2, s0
	s_xor_b32 s2, s2, 31
	s_lshl_b32 s3, s1, 5
	s_or_b32 s10, s2, s3
	s_and_b64 s[4:5], s[4:5], exec
	s_cselect_b32 s4, -1, s10
	s_ashr_i32 s5, s4, 31
	s_lshl_b64 s[6:7], s[4:5], 13
	v_readlane_b32 s8, v254, 41
	v_readlane_b32 s9, v254, 42
	s_add_u32 s6, s8, s6
	s_addc_u32 s7, s9, s7
	s_lshl_b32 s8, s4, 6
	s_ashr_i32 s9, s8, 31
	s_lshl_b64 s[8:9], s[8:9], 1
	v_readlane_b32 s12, v254, 43
	v_readlane_b32 s13, v254, 44
	s_add_u32 s8, s12, s8
	s_addc_u32 s9, s13, s9
	v_lshl_add_u64 v[2:3], s[6:7], 0, v[168:169]
	v_lshlrev_b32_e32 v170, 1, v110
	v_mov_b32_e32 v171, v0
	v_lshlrev_b64 v[4:5], 14, v[108:109]
	v_lshl_add_u64 v[2:3], v[2:3], 0, v[170:171]
	v_lshl_add_u64 v[4:5], s[8:9], 0, v[4:5]
	v_lshl_add_u64 v[4:5], v[4:5], 0, v[170:171]
	v_add_u32_e32 v1, 0, v241
	v_lshlrev_b32_e32 v2, 3, v108
	v_add_u32_e32 v172, v1, v242
	v_sub_u32_e32 v1, v1, v2
	s_movk_i32 s3, 0x2400
	v_add3_u32 v173, v1, v242, s3
	s_cmp_gt_i32 s4, -1
	v_mul_f32_e32 v166, 0x42000000, v208
	s_waitcnt vmcnt(1)
	ds_write_b128 v172, v[128:131]
	s_waitcnt vmcnt(0)
	ds_write2_b64 v173, v[132:133], v[134:135] offset1:1
	s_waitcnt lgkmcnt(0)
	s_barrier
	s_cbranch_scc1 .LBB0_989
	v_mul_f32_e32 v248, 0x42000000, v208
	s_mov_b64 s[4:5], 0
	s_branch .LBB0_990
